# prompt attention hot loop: all K fragments and V fragments prefetched from LDS before their MFMAs (was ds_read->wait->mfma x16)
# speedup vs baseline: 1.1309x; 1.0043x over previous
; #define LAS __attribute__((address_space(3)))
; __device__ __forceinline__ int crow(int r, int hi) { return (r & 3) + 8 * (r >> 2) + 4 * hi; }
; __device__ __forceinline__ void attn_tile(const LAS unsigned char* Kt, const LAS unsigned char* Vt, const LAS f32x4* ck, const bf16x8 (&qr)[4], const float cq2, const int kp0, const int qpos, const int qfirst, ...
;             f32x16 p0, p1;
;             const bool first = (m_run == -INFINITY);
;             const float cbase = first ? cq2 : cqm;
; #pragma unroll
;             for (int g = 0; g < 4; ++g) { const f32x4 c0 = ck[2 * g + hi], c1 = ck[8 + 2 * g + hi];
; #pragma unroll
;                 for (int i = 0; i < 4; ++i) { p0[4 * g + i] = cbase - c0[i]; p1[4 * g + i] = cbase - c1[i]; } }
; #pragma unroll
;             for (int d0 = 0; d0 < 4; ++d0) {
;                 const bf16x8 k0 = *(const LAS bf16x8*)(Kt + r32 * 144 + d0 * 32 + hi * 16), k1 = *(const LAS bf16x8*)(Kt + (32 + r32) * 144 + d0 * 32 + hi * 16);
;                 p0 = __builtin_amdgcn_mfma_f32_32x32x16_bf16(k0, qr[d0], p0, 0, 0, 0); p1 = __builtin_amdgcn_mfma_f32_32x32x16_bf16(k1, qr[d0], p1, 0, 0, 0); }
;             if (kp0 + 63 > qfirst) {
; #pragma unroll
;                 for (int r = 0; r < 16; ++r) { const int kk = kp0 + crow(r, hi); if (kk > qpos) p0[r] = -INFINITY; if (kk + 32 > qpos) p1[r] = -INFINITY; } }
.LBB0_472:
	s_cmp_gt_u32 s15, 32
	s_cbranch_scc1 .LBB0_482
	v_add_u32_e32 v185, v174, v120
	ds_read_b128 v[34:37], v178 offset:38912
	ds_read_b128 v[38:41], v178 offset:38944
	ds_read_b128 v[42:45], v178 offset:38976
	ds_read_b128 v[46:49], v178 offset:39008
	ds_read_b128 v[50:53], v178 offset:39040
	ds_read_b128 v[54:57], v178 offset:39072
	ds_read_b128 v[58:61], v178 offset:39104
	ds_read_b128 v[62:65], v178 offset:39136
	ds_read_b128 v[186:189], v185
	ds_read_b128 v[190:193], v185 offset:4608
	ds_read_b128 v[194:197], v185 offset:32
	ds_read_b128 v[198:201], v185 offset:4640
	ds_read_b128 v[202:205], v185 offset:64
	ds_read_b128 v[206:209], v185 offset:4672
	ds_read_b128 v[210:213], v185 offset:96
	v_cmp_eq_f32_e32 vcc, s37, v139
	s_add_i32 s0, s51, s14
	s_cmp_le_u32 s0, s24
	v_cndmask_b32_e32 v1, v184, v179, vcc
	s_waitcnt lgkmcnt(11)
	v_sub_f32_e32 v49, v1, v49
	v_sub_f32_e32 v48, v1, v48
	v_sub_f32_e32 v47, v1, v47
	v_sub_f32_e32 v46, v1, v46
	v_sub_f32_e32 v45, v1, v45
	v_sub_f32_e32 v44, v1, v44
	v_sub_f32_e32 v43, v1, v43
	v_sub_f32_e32 v42, v1, v42
	v_sub_f32_e32 v41, v1, v41
	v_sub_f32_e32 v40, v1, v40
	v_sub_f32_e32 v39, v1, v39
	v_sub_f32_e32 v38, v1, v38
	v_sub_f32_e32 v37, v1, v37
	v_sub_f32_e32 v36, v1, v36
	v_sub_f32_e32 v35, v1, v35
	v_sub_f32_e32 v34, v1, v34
	ds_read_b128 v[214:217], v185 offset:4704
	s_waitcnt lgkmcnt(8)
	v_sub_f32_e32 v65, v1, v65
	v_sub_f32_e32 v64, v1, v64
	v_sub_f32_e32 v63, v1, v63
	v_sub_f32_e32 v62, v1, v62
	v_sub_f32_e32 v61, v1, v61
	v_sub_f32_e32 v60, v1, v60
	v_sub_f32_e32 v59, v1, v59
	v_sub_f32_e32 v58, v1, v58
	v_sub_f32_e32 v57, v1, v57
	v_sub_f32_e32 v56, v1, v56
	v_sub_f32_e32 v55, v1, v55
	v_sub_f32_e32 v54, v1, v54
	v_sub_f32_e32 v53, v1, v53
	v_sub_f32_e32 v52, v1, v52
	v_sub_f32_e32 v51, v1, v51
	v_sub_f32_e32 v50, v1, v50
	v_cmp_neq_f32_e32 vcc, s37, v139
	s_waitcnt lgkmcnt(7)
	v_mfma_f32_32x32x16_bf16 v[34:49], v[186:189], v[108:111], v[34:49]
	s_waitcnt lgkmcnt(6)
	v_mfma_f32_32x32x16_bf16 v[50:65], v[190:193], v[108:111], v[50:65]
	s_waitcnt lgkmcnt(5)
	v_mfma_f32_32x32x16_bf16 v[34:49], v[194:197], v[104:107], v[34:49]
	s_waitcnt lgkmcnt(4)
	v_mfma_f32_32x32x16_bf16 v[50:65], v[198:201], v[104:107], v[50:65]
	s_waitcnt lgkmcnt(3)
	v_mfma_f32_32x32x16_bf16 v[34:49], v[202:205], v[100:103], v[34:49]
	s_waitcnt lgkmcnt(2)
	v_mfma_f32_32x32x16_bf16 v[50:65], v[206:209], v[100:103], v[50:65]
	s_waitcnt lgkmcnt(1)
	v_mfma_f32_32x32x16_bf16 v[34:49], v[210:213], v[96:99], v[34:49]
	s_waitcnt lgkmcnt(0)
	v_mfma_f32_32x32x16_bf16 v[50:65], v[214:217], v[96:99], v[50:65]
	s_cbranch_scc1 .LBB0_475
	v_add_u32_e32 v1, s14, v181
	v_cmp_le_u32_e64 s[0:1], v1, v172
	s_nop 8
	v_cndmask_b32_e64 v50, v137, v50, s[0:1]
	v_cmp_lt_u32_e64 s[0:1], v1, v180
	s_nop 1
	v_cndmask_b32_e64 v35, v137, v35, s[0:1]
	v_cmp_le_u32_e64 s[0:1], v1, v180
	s_nop 1
	v_cndmask_b32_e64 v34, v137, v34, s[0:1]
	v_cmp_le_u32_e64 s[0:1], v1, v171
	s_nop 1
	v_cndmask_b32_e64 v51, v137, v51, s[0:1]
	v_cmp_le_u32_e64 s[0:1], v1, v170
	s_nop 1
	v_cndmask_b32_e64 v36, v137, v36, s[0:1]
	v_cmp_le_u32_e64 s[0:1], v1, v169
	s_nop 1
	v_cndmask_b32_e64 v52, v137, v52, s[0:1]
	v_cmp_le_u32_e64 s[0:1], v1, v168
	s_nop 1
	v_cndmask_b32_e64 v37, v137, v37, s[0:1]
	v_cmp_le_u32_e64 s[0:1], v1, v167
	s_nop 1
	v_cndmask_b32_e64 v53, v137, v53, s[0:1]
	v_cmp_le_u32_e64 s[0:1], v1, v166
	s_nop 1
	v_cndmask_b32_e64 v38, v137, v38, s[0:1]
	v_cmp_le_u32_e64 s[0:1], v1, v165
	s_nop 1
	v_cndmask_b32_e64 v54, v137, v54, s[0:1]
	v_cmp_le_u32_e64 s[0:1], v1, v164
	s_nop 1
	v_cndmask_b32_e64 v39, v137, v39, s[0:1]
	v_cmp_le_u32_e64 s[0:1], v1, v163
	s_nop 1
	v_cndmask_b32_e64 v55, v137, v55, s[0:1]
	v_cmp_le_u32_e64 s[0:1], v1, v162
	s_nop 1
	v_cndmask_b32_e64 v40, v137, v40, s[0:1]
	v_cmp_le_u32_e64 s[0:1], v1, v161
	s_nop 1
	v_cndmask_b32_e64 v56, v137, v56, s[0:1]
	v_cmp_le_u32_e64 s[0:1], v1, v160
	s_nop 1
	v_cndmask_b32_e64 v41, v137, v41, s[0:1]
	v_cmp_le_u32_e64 s[0:1], v1, v159
	s_nop 1
	v_cndmask_b32_e64 v57, v137, v57, s[0:1]
	v_cmp_le_u32_e64 s[0:1], v1, v158
	s_nop 1
	v_cndmask_b32_e64 v42, v137, v42, s[0:1]
	v_cmp_le_u32_e64 s[0:1], v1, v157
	s_nop 1
	v_cndmask_b32_e64 v58, v137, v58, s[0:1]
	v_cmp_le_u32_e64 s[0:1], v1, v156
	s_nop 1
	v_cndmask_b32_e64 v43, v137, v43, s[0:1]
	v_cmp_le_u32_e64 s[0:1], v1, v155
	s_nop 1
	v_cndmask_b32_e64 v59, v137, v59, s[0:1]
	v_cmp_le_u32_e64 s[0:1], v1, v154
	s_nop 1
	v_cndmask_b32_e64 v44, v137, v44, s[0:1]
	v_cmp_le_u32_e64 s[0:1], v1, v153
	s_nop 1
	v_cndmask_b32_e64 v60, v137, v60, s[0:1]
	v_cmp_le_u32_e64 s[0:1], v1, v152
	s_nop 1
	v_cndmask_b32_e64 v45, v137, v45, s[0:1]
	v_cmp_le_u32_e64 s[0:1], v1, v151
	s_nop 1
	v_cndmask_b32_e64 v61, v137, v61, s[0:1]
	v_cmp_le_u32_e64 s[0:1], v1, v150
	s_nop 1
	v_cndmask_b32_e64 v46, v137, v46, s[0:1]
	v_cmp_le_u32_e64 s[0:1], v1, v149
	s_nop 1
	v_cndmask_b32_e64 v62, v137, v62, s[0:1]
	v_cmp_le_u32_e64 s[0:1], v1, v148
	s_nop 1
	v_cndmask_b32_e64 v47, v137, v47, s[0:1]
	v_cmp_le_u32_e64 s[0:1], v1, v147
	s_nop 1
	v_cndmask_b32_e64 v63, v137, v63, s[0:1]
	v_cmp_le_u32_e64 s[0:1], v1, v146
	s_nop 1
	v_cndmask_b32_e64 v48, v137, v48, s[0:1]
	v_cmp_le_u32_e64 s[0:1], v1, v145
	s_nop 1
	v_cndmask_b32_e64 v64, v137, v64, s[0:1]
	v_cmp_le_u32_e64 s[0:1], v1, v144
	s_nop 1
	v_cndmask_b32_e64 v49, v137, v49, s[0:1]
	v_cmp_le_u32_e64 s[0:1], v1, v143
	s_nop 1
	v_cndmask_b32_e64 v65, v137, v65, s[0:1]

; #define LAS __attribute__((address_space(3)))
; __device__ __forceinline__ unsigned cvt_pk_bf16(float lo, float hi) { unsigned r; asm volatile("v_cvt_pk_bf16_f32 %0, %1, %2" : "=v"(r) : "v"(lo), "v"(hi)); return r; }
; __device__ __forceinline__ void attn_tile(const LAS unsigned char* Kt, const LAS unsigned char* Vt, const LAS f32x4* ck, const bf16x8 (&qr)[4], const float cq2, const int kp0, const int qpos, const int qfirst, ...
;     ...
;             float ps = 0.f;
; #pragma unroll
;             for (int r = 0; r < 16; ++r) { p0[r] = __builtin_amdgcn_exp2f(p0[r]); p1[r] = __builtin_amdgcn_exp2f(p1[r]); ps += p0[r] + p1[r]; }
;             l_run += ps;
;             bf16x8 pa[4];
;             { u32x4 w;
;               w.x = cvt_pk_bf16(p0[0], p0[1]); w.y = cvt_pk_bf16(p0[2], p0[3]); w.z = cvt_pk_bf16(p0[4], p0[5]); w.w = cvt_pk_bf16(p0[6], p0[7]); pa[0] = __builtin_bit_cast(bf16x8, w);
;               w.x = cvt_pk_bf16(p0[8], p0[9]); w.y = cvt_pk_bf16(p0[10], p0[11]); w.z = cvt_pk_bf16(p0[12], p0[13]); w.w = cvt_pk_bf16(p0[14], p0[15]); pa[1] = __builtin_bit_cast(bf16x8, w);
;               w.x = cvt_pk_bf16(p1[0], p1[1]); w.y = cvt_pk_bf16(p1[2], p1[3]); w.z = cvt_pk_bf16(p1[4], p1[5]); w.w = cvt_pk_bf16(p1[6], p1[7]); pa[2] = __builtin_bit_cast(bf16x8, w);
;               w.x = cvt_pk_bf16(p1[8], p1[9]); w.y = cvt_pk_bf16(p1[10], p1[11]); w.z = cvt_pk_bf16(p1[12], p1[13]); w.w = cvt_pk_bf16(p1[14], p1[15]); pa[3] = __builtin_bit_cast(bf16x8, w); }
;             const LAS unsigned char* vbase = Vt + (4 * hi + ((lane & 15) >> 2)) * 160 + ((lane >> 4) & 1) * 32 + (lane & 3) * 8;
; #pragma unroll
;             for (int kk = 0; kk < 4; ++kk) {
; #pragma unroll
;                 for (int dh = 0; dh < 2; ++dh) {
;                     const v4i16_t lo = __builtin_amdgcn_ds_read_tr16_b64_v4i16((LAS v4i16_t*)(vbase + kk * 16 * 160 + dh * 64));
;                     const v4i16_t hv = __builtin_amdgcn_ds_read_tr16_b64_v4i16((LAS v4i16_t*)(vbase + kk * 16 * 160 + 8 * 160 + dh * 64));
;                     const bf16x8 vf = (bf16x8){lo[0], lo[1], lo[2], lo[3], hv[0], hv[1], hv[2], hv[3]};
;                     if (dh == 0) o0 = __builtin_amdgcn_mfma_f32_32x32x16_bf16(vf, pa[kk], o0, 0, 0, 0); else o1 = __builtin_amdgcn_mfma_f32_32x32x16_bf16(vf, pa[kk], o1, 0, 0, 0); } }
.LBB0_481:
	s_or_b64 exec, exec, s[0:1]
	v_add_u32_e32 v250, v140, v141
	ds_read_b64_tr_b16 v[218:219], v250 offset:18432
	ds_read_b64_tr_b16 v[220:221], v250 offset:19712
	ds_read_b64_tr_b16 v[222:223], v250 offset:18496
	ds_read_b64_tr_b16 v[224:225], v250 offset:19776
	ds_read_b64_tr_b16 v[226:227], v250 offset:20992
	ds_read_b64_tr_b16 v[228:229], v250 offset:22272
	ds_read_b64_tr_b16 v[230:231], v250 offset:21056
	ds_read_b64_tr_b16 v[232:233], v250 offset:22336
	ds_read_b64_tr_b16 v[234:235], v250 offset:23552
	ds_read_b64_tr_b16 v[236:237], v250 offset:24832
	ds_read_b64_tr_b16 v[238:239], v250 offset:23616
	ds_read_b64_tr_b16 v[240:241], v250 offset:24896
	ds_read_b64_tr_b16 v[242:243], v250 offset:26112
	ds_read_b64_tr_b16 v[244:245], v250 offset:27392
	v_exp_f32_e32 v1, v34
	v_exp_f32_e32 v185, v50
	v_exp_f32_e32 v188, v35
	v_exp_f32_e32 v189, v51
	v_exp_f32_e32 v190, v36
	v_exp_f32_e32 v191, v52
	v_exp_f32_e32 v192, v37
	v_exp_f32_e32 v193, v53
	v_add_f32_e32 v34, v185, v1
	v_add_f32_e32 v34, 0, v34
	v_add_f32_e32 v35, v189, v188
	v_add_f32_e32 v34, v35, v34
	v_add_f32_e32 v35, v191, v190
	v_add_f32_e32 v34, v35, v34
	v_add_f32_e32 v35, v193, v192
	v_add_f32_e32 v50, v35, v34
	v_exp_f32_e32 v35, v38
	v_exp_f32_e32 v37, v54
	v_exp_f32_e32 v34, v39
	v_exp_f32_e32 v36, v55
	v_exp_f32_e32 v51, v40
	v_exp_f32_e32 v53, v56
	v_exp_f32_e32 v52, v57
	v_pk_add_f32 v[38:39], v[36:37], v[34:35]
	v_exp_f32_e32 v55, v42
	v_add_f32_e32 v39, v39, v50
	v_exp_f32_e32 v50, v41
	v_add_f32_e32 v54, v38, v39
	v_exp_f32_e32 v57, v58
	v_exp_f32_e32 v56, v59
	v_pk_add_f32 v[38:39], v[52:53], v[50:51]
	v_exp_f32_e32 v59, v44
	v_add_f32_e32 v39, v39, v54
	v_exp_f32_e32 v54, v43
	v_exp_f32_e32 v187, v60
	v_exp_f32_e32 v58, v45
	v_exp_f32_e32 v186, v61
	v_add_f32_e32 v40, v38, v39
	v_pk_add_f32 v[38:39], v[56:57], v[54:55]
	v_exp_f32_e32 v45, v46
	v_exp_f32_e32 v61, v62
	v_exp_f32_e32 v44, v47
	v_exp_f32_e32 v60, v63
	v_add_f32_e32 v39, v39, v40
	v_add_f32_e32 v40, v38, v39
	v_pk_add_f32 v[38:39], v[186:187], v[58:59]
	v_exp_f32_e32 v47, v48
	v_exp_f32_e32 v63, v64
	v_exp_f32_e32 v46, v49
	v_exp_f32_e32 v62, v65
	v_add_f32_e32 v39, v39, v40
	v_add_f32_e32 v40, v38, v39
	v_pk_add_f32 v[38:39], v[60:61], v[44:45]
	s_nop 0
	v_add_f32_e32 v39, v39, v40
	v_add_f32_e32 v40, v38, v39
	v_pk_add_f32 v[38:39], v[62:63], v[46:47]
	s_nop 0
	v_add_f32_e32 v39, v39, v40
	v_add_f32_e32 v38, v38, v39
	v_add_f32_e32 v118, v118, v38
	v_cvt_pk_bf16_f32 v38, v1, v188
	s_waitcnt lgkmcnt(13)
	ds_read_b64_tr_b16 v[246:247], v250 offset:26176
	ds_read_b64_tr_b16 v[248:249], v250 offset:27456
	v_cvt_pk_bf16_f32 v39, v190, v192
	v_cvt_pk_bf16_f32 v40, v35, v34
	v_cvt_pk_bf16_f32 v41, v51, v50
	v_cvt_pk_bf16_f32 v42, v55, v54
	v_cvt_pk_bf16_f32 v43, v59, v58
	v_cvt_pk_bf16_f32 v44, v45, v44
	v_cvt_pk_bf16_f32 v45, v47, v46
	v_cvt_pk_bf16_f32 v46, v185, v189
	v_cvt_pk_bf16_f32 v47, v191, v193
	v_cvt_pk_bf16_f32 v48, v37, v36
	v_cvt_pk_bf16_f32 v49, v53, v52
	v_cvt_pk_bf16_f32 v34, v57, v56
	v_cvt_pk_bf16_f32 v35, v187, v186
	v_cvt_pk_bf16_f32 v36, v61, v60
	v_cvt_pk_bf16_f32 v37, v63, v62
	s_waitcnt lgkmcnt(0)
	v_mfma_f32_32x32x16_bf16 v[18:33], v[218:221], v[38:41], v[18:33]
	v_mfma_f32_32x32x16_bf16 v[2:17], v[222:225], v[38:41], v[2:17]
	v_mfma_f32_32x32x16_bf16 v[18:33], v[226:229], v[42:45], v[18:33]
	v_mfma_f32_32x32x16_bf16 v[2:17], v[230:233], v[42:45], v[2:17]
	v_mfma_f32_32x32x16_bf16 v[18:33], v[234:237], v[46:49], v[18:33]
	v_mfma_f32_32x32x16_bf16 v[2:17], v[238:241], v[46:49], v[2:17]
	v_mfma_f32_32x32x16_bf16 v[18:33], v[242:245], v[34:37], v[18:33]
	v_mfma_f32_32x32x16_bf16 v[2:17], v[246:249], v[34:37], v[2:17]
